# rotation extended: active-tile test and DMA slot setup also computed in front of the loop barrier
# baseline (speedup 1.0000x reference)
; template <bool DIFF> ...
;     ...
;     bf16x8 bq[KS];
; #pragma unroll
;     for (int f = 0; f < KS; ++f) bq[f] = *(const bf16x8*)(qrow + mp * 64 + f * 16 + h * 8);
;     float m_ = -INFINITY; f32x16 O[4], lacc;
;     const bf16x8 ones = {0x3F80, 0x3F80, 0x3F80, 0x3F80, 0x3F80, 0x3F80, 0x3F80, 0x3F80};
; #pragma unroll
;     for (int ii = 0; ii < 16; ++ii) lacc[ii] = 0.f;
; #pragma unroll
;     for (int db = 0; db < 4; ++db)
; #pragma unroll
;         for (int ii = 0; ii < 16; ++ii) O[db][ii] = 0.f;
;     int goff[5];
; #pragma unroll
;     for (int i = 0; i < 5; ++i) { int op = wave + 8 * i; op = op > 36 ? 36 : op; const bool isk = op < 17; const int slot = (isk ? op : op - 17) * 64 + lane; const int per = isk ? 17 : 20;
;         const int row = slot / per; int pcs = slot - row * per; pcs = pcs > 15 ? 15 : pcs; goff[i] = (row << 10) | (pcs << 4); }
.LBB0_1479:
	v_readfirstlane_b32 s42, v2
	v_readfirstlane_b32 s43, v3
	v_readfirstlane_b32 s40, v4
	v_readfirstlane_b32 s41, v5
	v_readfirstlane_b32 s89, v176
	s_lshr_b32 s86, s89, 6
	s_bfe_u32 s87, s89, 0x10006
	s_lshl_b32 s94, s87, 7
	s_min_u32 s0, s86, 36
	s_cmpk_lt_u32 s89, 0x440
	s_cselect_b64 s[6:7], -1, 0
	s_lshl_b32 s1, s0, 6
	s_add_i32 s8, s1, 0xfffffbc0
	s_and_b64 s[4:5], s[6:7], exec
	v_lshl_add_u64 v[6:7], v[6:7], 0, s[94:95]
	v_lshlrev_b32_e32 v0, 1, v144
	s_cselect_b32 s1, s1, s8
	s_cselect_b32 s4, 17, 20
	v_lshl_add_u64 v[6:7], v[6:7], 0, v[0:1]
	v_or_b32_e32 v0, s1, v206
	v_cvt_f32_ubyte0_e32 v10, s4
	v_cvt_f32_i32_e32 v8, v0
	v_rcp_iflag_f32_e32 v11, v10
	global_load_dwordx4 v[128:131], v[6:7], off
	global_load_dwordx4 v[132:135], v[6:7], off offset:32
	global_load_dwordx4 v[136:139], v[6:7], off offset:64
	global_load_dwordx4 v[140:143], v[6:7], off offset:96
	s_ashr_i32 s1, s1, 30
	v_mul_f32_e32 v6, v8, v11
	v_trunc_f32_e32 v6, v6
	s_or_b32 s1, s1, 1
	v_fma_f32 v7, -v6, v10, v8
	v_cvt_i32_f32_e32 v6, v6
	v_mov_b32_e32 v8, s1
	s_min_u32 s1, s86, 28
	v_cmp_ge_f32_e64 vcc, |v7|, v10
	s_add_i32 s12, s1, 8
	s_cmpk_lt_u32 s89, 0x240
	v_cndmask_b32_e32 v7, 0, v8, vcc
	v_add_u32_e32 v6, v6, v7
	s_cselect_b64 s[8:9], -1, 0
	s_lshl_b32 s1, s12, 6
	v_bfe_i32 v6, v6, 0, 14
	s_add_i32 s10, s1, 0xfffffbc0
	v_mul_i32_i24_e32 v7, s4, v6
	s_and_b64 s[4:5], s[8:9], exec
	s_cselect_b32 s1, s1, s10
	s_cselect_b32 s4, 17, 20
	v_or_b32_e32 v8, s1, v206
	v_cvt_f32_ubyte0_e32 v11, s4
	v_cvt_f32_i32_e32 v10, v8
	v_rcp_iflag_f32_e32 v12, v11
	s_ashr_i32 s1, s1, 30
	s_or_b32 s1, s1, 1
	v_mov_b32_e32 v13, s1
	v_mul_f32_e32 v12, v10, v12
	v_trunc_f32_e32 v12, v12
	v_fma_f32 v10, -v12, v11, v10
	v_cvt_i32_f32_e32 v12, v12
	v_cmp_ge_f32_e64 vcc, |v10|, v11
	s_min_u32 s1, s86, 20
	s_add_i32 s13, s1, 16
	v_cndmask_b32_e32 v10, 0, v13, vcc
	v_add_u32_e32 v10, v12, v10
	s_cmp_lt_u32 s89, 64
	v_bfe_i32 v10, v10, 0, 14
	s_cselect_b64 s[10:11], -1, 0
	s_lshl_b32 s1, s13, 6
	v_mul_i32_i24_e32 v11, s4, v10
	s_addk_i32 s1, 0xfbc0
	v_sub_u32_e32 v8, v8, v11
	s_and_b64 s[4:5], s[10:11], exec
	v_min_i32_e32 v8, 15, v8
	s_cselect_b32 s1, 0x400, s1
	s_cselect_b32 s4, 17, 20
	v_lshlrev_b32_e32 v12, 4, v8
	v_or_b32_e32 v8, s1, v206
	v_cvt_f32_ubyte0_e32 v13, s4
	v_cvt_f32_i32_e32 v11, v8
	v_rcp_iflag_f32_e32 v14, v13
	v_lshl_or_b32 v15, v10, 10, v12
	s_ashr_i32 s1, s1, 30
	s_or_b32 s1, s1, 1
	v_mul_f32_e32 v10, v11, v14
	v_trunc_f32_e32 v10, v10
	v_fma_f32 v11, -v10, v13, v11
	v_cvt_i32_f32_e32 v10, v10
	v_mov_b32_e32 v14, s1
	v_cmp_ge_f32_e64 vcc, |v11|, v13
	s_min_u32 s1, s86, 12
	s_movk_i32 s14, 0xffec
	v_cndmask_b32_e32 v11, 0, v14, vcc
	v_add_u32_e32 v10, v10, v11
	v_bfe_i32 v10, v10, 0, 14
	v_mul_i32_i24_e32 v11, s4, v10
	v_sub_u32_e32 v8, v8, v11
	v_min_i32_e32 v8, 15, v8
	s_add_i32 s4, s1, 24
	v_lshlrev_b32_e32 v14, 4, v8
	v_lshl_add_u32 v8, s4, 6, v145
	v_lshl_or_b32 v16, v10, 10, v14
	v_mul_u32_u24_e32 v10, 0xcccd, v8
	v_lshrrev_b32_e32 v11, 20, v10
	v_mad_i32_i24 v8, v11, s14, v8
	s_min_u32 s1, s86, 4
	v_min_i32_e32 v8, 15, v8
	s_or_b32 s5, s1, 32
	v_lshrrev_b32_e32 v10, 10, v10
	v_lshlrev_b32_e32 v17, 4, v8
	v_lshl_add_u32 v8, s5, 6, v145
	v_sub_u32_e32 v0, v0, v7
	v_or_b32_e32 v18, v17, v10
	v_mul_u32_u24_e32 v10, 0xcccd, v8
	v_min_i32_e32 v0, 15, v0
	v_lshrrev_b32_e32 v11, 20, v10
	v_lshlrev_b32_e32 v0, 4, v0
	v_mad_i32_i24 v8, v11, s14, v8
	v_lshl_or_b32 v6, v6, 10, v0
	v_min_i32_e32 v8, 15, v8
	v_lshrrev_b32_e32 v10, 10, v10
	v_lshlrev_b32_e32 v19, 4, v8
	s_add_i32 s83, s81, -1
	v_ashrrev_i32_e32 v21, 10, v6
	v_or_b32_e32 v20, v19, v10
	v_min_i32_e32 v10, s83, v21
	s_lshl_b32 s14, s0, 10
	v_ashrrev_i32_e32 v11, 31, v10
	s_add_i32 s15, s14, 0x8800
	v_cndmask_b32_e64 v9, v3, v5, s[6:7]
	v_cndmask_b32_e64 v8, v2, v4, s[6:7]
	v_lshlrev_b64 v[10:11], 10, v[10:11]
	s_and_b64 s[0:1], s[6:7], exec
	v_lshl_add_u64 v[10:11], v[8:9], 0, v[10:11]
	v_and_b32_e32 v0, 0x3f0, v0
	s_cselect_b32 s0, s14, s15
	s_barrier
; template <bool DIFF> ...
;     ...
;     for (int t = 0; t < NT; ++t) {
;         const int k3n = (k3 == 2) ? 0 : k3 + 1;
;         if (t + 1 < NT) A_DMA(t + 1, k3n, (t + 1) & 3);
;         if (late && pact) A_PV((t - 1) & 3);
;         const bool active = split ? ((t % NG) == grp) : (t <= my_lim);
	s_waitcnt vmcnt(0)
	v_lshl_add_u64 v[10:11], v[10:11], 0, v[0:1]
	s_add_i32 m0, s0, 0
	v_ashrrev_i32_e32 v22, 10, v15
	global_load_lds_dwordx4 v[10:11], off
	v_min_i32_e32 v10, s83, v22
	s_lshl_b32 s12, s12, 10
	v_ashrrev_i32_e32 v11, 31, v10
	s_add_i32 s15, s12, 0x8800
	v_cndmask_b32_e64 v7, v3, v5, s[8:9]
	v_cndmask_b32_e64 v6, v2, v4, s[8:9]
	v_lshlrev_b64 v[10:11], 10, v[10:11]
	s_and_b64 s[0:1], s[8:9], exec
	v_lshl_add_u64 v[10:11], v[6:7], 0, v[10:11]
	v_and_b32_e32 v12, 0x3f0, v12
	v_mov_b32_e32 v13, v1
	s_cselect_b32 s0, s12, s15
	v_lshl_add_u64 v[10:11], v[10:11], 0, v[12:13]
	s_add_i32 m0, s0, 0
	v_ashrrev_i32_e32 v23, 10, v16
	global_load_lds_dwordx4 v[10:11], off
	v_min_i32_e32 v10, s83, v23
	s_lshl_b32 s13, s13, 10
	v_ashrrev_i32_e32 v11, 31, v10
	s_add_i32 s15, s13, 0x8800
	v_cndmask_b32_e64 v5, v3, v5, s[10:11]
	v_cndmask_b32_e64 v4, v2, v4, s[10:11]
	v_lshlrev_b64 v[10:11], 10, v[10:11]
	s_and_b64 s[0:1], s[10:11], exec
	v_lshl_add_u64 v[10:11], v[4:5], 0, v[10:11]
	v_and_b32_e32 v14, 0x3f0, v14
	v_mov_b32_e32 v15, v1
	s_cselect_b32 s0, 0x4000, s15
	v_lshl_add_u64 v[10:11], v[10:11], 0, v[14:15]
	s_add_i32 m0, s0, 0
	v_ashrrev_i32_e32 v24, 10, v18
	global_load_lds_dwordx4 v[10:11], off
	v_min_i32_e32 v10, s83, v24
	v_ashrrev_i32_e32 v11, 31, v10
	v_lshlrev_b64 v[10:11], 10, v[10:11]
	s_lshl_b32 s0, s4, 10
	v_lshl_add_u64 v[10:11], v[2:3], 0, v[10:11]
	v_and_b32_e32 v16, 0x3f0, v17
	v_mov_b32_e32 v17, v1
	s_add_i32 s4, s0, 0
	v_lshl_add_u64 v[10:11], v[10:11], 0, v[16:17]
	s_add_i32 m0, s4, 0x8800
	v_ashrrev_i32_e32 v20, 10, v20
	global_load_lds_dwordx4 v[10:11], off
	v_min_i32_e32 v10, s83, v20
	v_ashrrev_i32_e32 v11, 31, v10
	v_lshlrev_b64 v[10:11], 10, v[10:11]
	s_lshl_b32 s0, s5, 10
	v_lshl_add_u64 v[10:11], v[2:3], 0, v[10:11]
	v_and_b32_e32 v18, 0x3f0, v19
	v_mov_b32_e32 v19, v1
	s_add_i32 s5, s0, 0
	v_lshl_add_u64 v[10:11], v[10:11], 0, v[18:19]
	s_add_i32 m0, s5, 0x8800
	v_mov_b32_e32 v178, v14
	global_load_lds_dwordx4 v[10:11], off
	s_waitcnt vmcnt(0) lgkmcnt(0)
	s_barrier
	v_mov_b32_e32 v14, v1
	v_mov_b32_e32 v172, v0
	v_mov_b32_e32 v174, v12
	v_mov_b32_e32 v180, v16
	v_mov_b32_e32 v182, v18
	v_add_u32_e32 v155, 64, v20
	v_add_u32_e32 v157, 64, v24
	v_add_u32_e32 v159, 64, v23
	v_add_u32_e32 v161, 64, v22
	v_add_u32_e32 v163, 64, v21
	v_mov_b32_e32 v0, v1
	v_mov_b32_e32 v2, v1
	v_mov_b32_e32 v3, v1
	v_mov_b32_e32 v4, v1
	v_mov_b32_e32 v5, v1
	v_mov_b32_e32 v6, v1
	v_mov_b32_e32 v7, v1
	v_mov_b32_e32 v8, v1
	v_mov_b32_e32 v9, v1
	v_mov_b32_e32 v10, v1
	v_mov_b32_e32 v11, v1
	v_mov_b32_e32 v12, v1
	v_mov_b64_e32 v[46:47], v[14:15]
	v_mov_b64_e32 v[30:31], v[14:15]
	v_mov_b64_e32 v[62:63], v[14:15]
	v_mov_b64_e32 v[78:79], v[14:15]
	v_mov_b64_e32 v[94:95], v[14:15]
	s_mov_b32 s0, 0
	s_lshr_b32 s88, s89, 7
	s_sub_i32 s1, s81, 64
	s_add_i32 s90, s14, 0
	s_add_i32 s92, s12, 0
	s_add_i32 s93, s13, 0
	v_add_u32_e32 v148, s94, v208
	s_mov_b64 s[12:13], -1
	v_mov_b32_e32 v153, 0xff800000
	v_mov_b64_e32 v[44:45], v[12:13]
	v_mov_b64_e32 v[42:43], v[10:11]
	v_mov_b64_e32 v[40:41], v[8:9]
	v_mov_b64_e32 v[38:39], v[6:7]
	v_mov_b64_e32 v[36:37], v[4:5]
	v_mov_b64_e32 v[34:35], v[2:3]
	v_mov_b64_e32 v[32:33], v[0:1]
	v_mov_b64_e32 v[28:29], v[12:13]
	v_mov_b64_e32 v[26:27], v[10:11]
	v_mov_b64_e32 v[24:25], v[8:9]
	v_mov_b64_e32 v[22:23], v[6:7]
	v_mov_b64_e32 v[20:21], v[4:5]
	v_mov_b64_e32 v[18:19], v[2:3]
	v_mov_b64_e32 v[16:17], v[0:1]
	v_mov_b64_e32 v[60:61], v[12:13]
	v_mov_b64_e32 v[58:59], v[10:11]
	v_mov_b64_e32 v[56:57], v[8:9]
	v_mov_b64_e32 v[54:55], v[6:7]
	v_mov_b64_e32 v[52:53], v[4:5]
	v_mov_b64_e32 v[50:51], v[2:3]
	v_mov_b64_e32 v[48:49], v[0:1]
	v_mov_b64_e32 v[76:77], v[12:13]
	v_mov_b64_e32 v[74:75], v[10:11]
	v_mov_b64_e32 v[72:73], v[8:9]
	v_mov_b64_e32 v[70:71], v[6:7]
	v_mov_b64_e32 v[68:69], v[4:5]
	v_mov_b64_e32 v[66:67], v[2:3]
	v_mov_b64_e32 v[64:65], v[0:1]
	v_mov_b64_e32 v[92:93], v[12:13]
	v_mov_b64_e32 v[90:91], v[10:11]
	v_mov_b64_e32 v[88:89], v[8:9]
	v_mov_b64_e32 v[86:87], v[6:7]
	v_mov_b64_e32 v[84:85], v[4:5]
	v_mov_b64_e32 v[82:83], v[2:3]
	v_mov_b64_e32 v[80:81], v[0:1]
	s_mov_b32 s14, 0
	s_mov_b32 s15, 0
	s_waitcnt vmcnt(0)
	s_and_b64 s[16:17], s[6:7], exec
	s_cselect_b64 s[44:45], s[40:41], s[42:43]
	s_and_b64 s[16:17], s[8:9], exec
	s_cselect_b64 s[46:47], s[40:41], s[42:43]
	s_and_b64 s[16:17], s[10:11], exec
	s_cselect_b64 s[48:49], s[40:41], s[42:43]
	v_mov_b32_e32 v240, 0
	v_mov_b32_e32 v241, 0
	v_mov_b32_e32 v242, 0
	v_mov_b32_e32 v243, 0
	s_add_i32 s16, s14, 1
	s_cmp_lg_u32 s14, 2
	s_cselect_b32 s84, s16, 0
	s_mul_i32 s16, s14, 0x4400
	v_add_u32_e32 v0, s16, v148
	s_add_i32 s85, s15, 1
	s_and_b32 s77, s15, 3
	s_cmp_eq_u32 s77, s88
	s_cselect_b32 s16, 1, 0
	s_cmp_le_i32 s15, s82
	s_cselect_b32 s17, 1, 0
	s_and_b64 s[78:79], exec, s[2:3]
	s_cselect_b32 s15, s16, s17
	s_bitcmp1_b32 s15, 0
	s_cselect_b64 s[78:79], -1, 0
	s_and_b32 s16, s85, 3
	s_mulk_i32 s16, 0x5000
	s_add_i32 s18, s16, 0x8800
	s_mul_i32 s19, s84, 0x4400
	s_branch .Lattn_head_nobar

; #define LAS __attribute__((address_space(3)))
; __device__ __forceinline__ int crow(int reg, int h) { return (reg & 3) + 8 * (reg >> 2) + 4 * h; }
; #define MFMA32(a, b, c) __builtin_amdgcn_mfma_f32_32x32x16_bf16((a), (b), (c), 0, 0, 0)
; template <bool DIFF> ...
;     ...
;         if (t + 1 < NT) A_DMA(t + 1, k3n, (t + 1) & 3);
;         if (late && pact) A_PV((t - 1) & 3);
;         const bool active = split ? ((t % NG) == grp) : (t <= my_lim);
;         if (active) {
;             const LAS unsigned char* kbuf = lds + A_KB + k3 * 17408 + mp * 128;
;             const float cin = first ? 0.f : -m_;
;             f32x16 s0, s1;
; #pragma unroll
;             for (int ii = 0; ii < 16; ++ii) { s0[ii] = cin; s1[ii] = cin; }
; #pragma unroll
;             for (int ks = 0; ks < KS; ++ks) {
;                 const bf16x8 a0 = *(const LAS bf16x8*)(kbuf + r * 272 + (ks * 16 + h * 8) * 2);
;                 const bf16x8 a1 = *(const LAS bf16x8*)(kbuf + (32 + r) * 272 + (ks * 16 + h * 8) * 2);
;                 s0 = MFMA32(a0, bq[ks], s0); s1 = MFMA32(a1, bq[ks], s1);
;             }
;             if (t * 64 + 64 > nkeys) {
; #pragma unroll
;                 for (int ii = 0; ii < 16; ++ii) { const int key = t * 64 + crow(ii, h); if (key >= nkeys) s0[ii] = -INFINITY; if (key + 32 >= nkeys) s1[ii] = -INFINITY; }
.Lattn_head_nobar:
	ds_read_b128 v[2:5], v0
	ds_read_b128 v[10:13], v0 offset:8704
	ds_read_b128 v[6:9], v0 offset:32
	ds_read_b128 v[212:215], v0 offset:8736
	ds_read_b128 v[216:219], v0 offset:64
	ds_read_b128 v[224:227], v0 offset:8768
	ds_read_b128 v[220:223], v0 offset:96
	ds_read_b128 v[228:231], v0 offset:8800
	s_cmp_ge_u32 s85, s80
	s_cbranch_scc1 .LBB0_1482
	v_add_u32_e32 v0, s0, v163
	v_add_u32_e32 v14, s0, v161
	v_min_i32_e32 v0, s83, v0
	v_min_i32_e32 v14, s83, v14
	v_lshl_add_u32 v0, v0, 10, v172
	v_lshl_add_u32 v14, v14, 10, v174
	s_and_b64 s[16:17], s[6:7], exec
	s_cselect_b32 s16, s19, s18
	s_add_i32 m0, s90, s16
	s_nop 0
	global_load_lds_dwordx4 v0, s[44:45]
	s_and_b64 s[16:17], s[8:9], exec
	s_cselect_b32 s16, s19, s18
	s_add_i32 m0, s92, s16
	v_add_u32_e32 v15, s0, v159
	global_load_lds_dwordx4 v14, s[46:47]
	v_min_i32_e32 v15, s83, v15
	v_lshl_add_u32 v15, v15, 10, v178
	s_and_b64 s[16:17], s[10:11], exec
	s_cselect_b32 s16, s19, s18
	s_add_i32 m0, s93, s16
	v_add_u32_e32 v0, s0, v157
	global_load_lds_dwordx4 v15, s[48:49]
	v_min_i32_e32 v0, s83, v0
	v_lshl_add_u32 v0, v0, 10, v180
	s_add_i32 m0, s18, s4
	v_add_u32_e32 v14, s0, v155
	global_load_lds_dwordx4 v0, s[42:43]
	v_min_i32_e32 v14, s83, v14
	v_lshl_add_u32 v14, v14, 10, v182
	s_add_i32 m0, s18, s5
	s_nop 0
	global_load_lds_dwordx4 v14, s[42:43]
.LBB0_1482:
	s_bitcmp0_b32 s15, 0
	s_cbranch_scc1 .LBB0_1493
	s_cmp_le_u32 s0, s1
	s_waitcnt lgkmcnt(0)
	v_mfma_f32_32x32x16_bf16 v[112:127], v[2:5], v[128:131], v[80:95]
	v_mfma_f32_32x32x16_bf16 v[96:111], v[10:13], v[128:131], v[80:95]
	v_mfma_f32_32x32x16_bf16 v[112:127], v[6:9], v[132:135], v[112:127]
	v_mfma_f32_32x32x16_bf16 v[96:111], v[212:215], v[132:135], v[96:111]
	v_mfma_f32_32x32x16_bf16 v[112:127], v[216:219], v[136:139], v[112:127]
	v_mfma_f32_32x32x16_bf16 v[96:111], v[224:227], v[136:139], v[96:111]
	v_mfma_f32_32x32x16_bf16 v[112:127], v[220:223], v[140:143], v[112:127]
	v_mfma_f32_32x32x16_bf16 v[96:111], v[228:231], v[140:143], v[96:111]
	s_cbranch_scc1 .LBB0_1485
	v_add_u32_e32 v0, s0, v177
	v_add_u32_e32 v2, 32, v0
	v_cmp_gt_u32_e32 vcc, s81, v2
	v_add_u32_e32 v2, 1, v0
	v_cmp_gt_u32_e64 s[44:45], s81, v2
	v_add_u32_e32 v2, 33, v0
	v_cmp_gt_u32_e64 s[14:15], s81, v2
	v_add_u32_e32 v2, 2, v0
	v_cmp_gt_u32_e64 s[48:49], s81, v2
	v_add_u32_e32 v2, 34, v0
	v_cmp_gt_u32_e64 s[16:17], s81, v2
	v_add_u32_e32 v2, 3, v0
	v_cmp_gt_u32_e64 s[50:51], s81, v2
	v_add_u32_e32 v2, 35, v0
	v_cmp_gt_u32_e64 s[18:19], s81, v2
	v_add_u32_e32 v2, 8, v0
	v_cmp_gt_u32_e64 s[52:53], s81, v2
	v_add_u32_e32 v2, 40, v0
	v_cmp_gt_u32_e64 s[20:21], s81, v2
	v_add_u32_e32 v2, 9, v0
	v_cmp_gt_u32_e64 s[54:55], s81, v2
	v_add_u32_e32 v2, 41, v0
	v_cmp_gt_u32_e64 s[22:23], s81, v2
	v_add_u32_e32 v2, 10, v0
	v_cmp_gt_u32_e64 s[56:57], s81, v2
	v_add_u32_e32 v2, 42, v0
	v_cmp_gt_u32_e64 s[24:25], s81, v2
	v_add_u32_e32 v2, 11, v0
	v_cmp_gt_u32_e64 s[58:59], s81, v2
	v_add_u32_e32 v2, 43, v0
	v_cmp_gt_u32_e64 s[26:27], s81, v2
	v_add_u32_e32 v2, 16, v0
	v_cmp_gt_u32_e64 s[60:61], s81, v2
	v_add_u32_e32 v2, 48, v0
	v_cmp_gt_u32_e64 s[28:29], s81, v2
	v_add_u32_e32 v2, 17, v0
	v_cmp_gt_u32_e64 s[62:63], s81, v2
	v_add_u32_e32 v2, 49, v0
	v_cmp_gt_u32_e64 s[30:31], s81, v2
	v_add_u32_e32 v2, 18, v0
	v_cmp_gt_u32_e64 s[64:65], s81, v2
	v_add_u32_e32 v2, 50, v0
	v_cmp_gt_u32_e64 s[34:35], s81, v2
	v_add_u32_e32 v2, 19, v0
	v_cmp_gt_u32_e64 s[66:67], s81, v2
	v_add_u32_e32 v2, 51, v0
	v_cmp_gt_u32_e64 s[36:37], s81, v2
	v_add_u32_e32 v2, 24, v0
	v_cmp_gt_u32_e64 s[68:69], s81, v2
	v_add_u32_e32 v2, 56, v0
	v_cmp_gt_u32_e64 s[38:39], s81, v2
	v_add_u32_e32 v2, 25, v0
	v_cmp_gt_u32_e64 s[70:71], s81, v2
	v_add_u32_e32 v2, 57, v0
	v_cmp_gt_u32_e64 s[42:43], s81, v2
	v_add_u32_e32 v2, 26, v0
	v_cmp_gt_u32_e64 s[72:73], s81, v2
	v_add_u32_e32 v2, 58, v0
	v_cmp_gt_u32_e64 s[46:47], s81, v2
	v_add_u32_e32 v2, 27, v0
	v_cmp_gt_u32_e64 s[74:75], s81, v2
	s_or_b64 s[72:73], s[74:75], s[72:73]
	s_or_b64 s[70:71], s[72:73], s[70:71]
	s_or_b64 s[68:69], s[70:71], s[68:69]
	s_or_b64 s[66:67], s[68:69], s[66:67]
	s_or_b64 s[64:65], s[66:67], s[64:65]
	s_or_b64 s[62:63], s[64:65], s[62:63]
	s_or_b64 s[60:61], s[62:63], s[60:61]
	s_or_b64 s[58:59], s[60:61], s[58:59]
	s_or_b64 s[56:57], s[58:59], s[56:57]
	s_or_b64 s[54:55], s[56:57], s[54:55]
	s_or_b64 s[52:53], s[54:55], s[52:53]
	s_or_b64 s[50:51], s[52:53], s[50:51]
	s_or_b64 s[48:49], s[50:51], s[48:49]
	v_cmp_gt_u32_e64 s[40:41], s81, v0
	s_or_b64 s[44:45], s[48:49], s[44:45]
	s_or_b64 s[40:41], s[44:45], s[40:41]
	v_add_u32_e32 v0, 59, v0
	v_cndmask_b32_e64 v112, v211, v112, s[40:41]
	v_cmp_gt_u32_e64 s[40:41], s81, v0
	v_cndmask_b32_e64 v127, v211, v127, s[74:75]
	v_cndmask_b32_e64 v126, v211, v126, s[72:73]
	v_cndmask_b32_e64 v111, v211, v111, s[40:41]
	s_or_b64 s[40:41], s[40:41], s[46:47]
	v_cndmask_b32_e64 v110, v211, v110, s[40:41]
	s_or_b64 s[40:41], s[40:41], s[42:43]
	s_or_b64 s[38:39], s[40:41], s[38:39]
	s_or_b64 s[36:37], s[38:39], s[36:37]
	s_or_b64 s[34:35], s[36:37], s[34:35]
	s_or_b64 s[30:31], s[34:35], s[30:31]
	s_or_b64 s[28:29], s[30:31], s[28:29]
	s_or_b64 s[26:27], s[28:29], s[26:27]
	s_or_b64 s[24:25], s[26:27], s[24:25]
	s_or_b64 s[22:23], s[24:25], s[22:23]
	s_or_b64 s[20:21], s[22:23], s[20:21]
	s_or_b64 s[18:19], s[20:21], s[18:19]
	s_or_b64 s[16:17], s[18:19], s[16:17]
	s_or_b64 s[14:15], s[16:17], s[14:15]
	s_or_b64 vcc, s[14:15], vcc
	v_cndmask_b32_e64 v125, v211, v125, s[70:71]
	v_cndmask_b32_e64 v124, v211, v124, s[68:69]
	v_cndmask_b32_e64 v123, v211, v123, s[66:67]
	v_cndmask_b32_e64 v122, v211, v122, s[64:65]
	v_cndmask_b32_e64 v121, v211, v121, s[62:63]
	v_cndmask_b32_e64 v120, v211, v120, s[60:61]
	v_cndmask_b32_e64 v119, v211, v119, s[58:59]
	v_cndmask_b32_e64 v118, v211, v118, s[56:57]
	v_cndmask_b32_e64 v117, v211, v117, s[54:55]
	v_cndmask_b32_e64 v116, v211, v116, s[52:53]
	v_cndmask_b32_e64 v115, v211, v115, s[50:51]
	v_cndmask_b32_e64 v114, v211, v114, s[48:49]
	v_cndmask_b32_e64 v113, v211, v113, s[44:45]
	v_cndmask_b32_e64 v109, v211, v109, s[40:41]
	v_cndmask_b32_e64 v108, v211, v108, s[38:39]
	v_cndmask_b32_e64 v107, v211, v107, s[36:37]
	v_cndmask_b32_e64 v106, v211, v106, s[34:35]
	v_cndmask_b32_e64 v105, v211, v105, s[30:31]
	v_cndmask_b32_e64 v104, v211, v104, s[28:29]
	v_cndmask_b32_e64 v103, v211, v103, s[26:27]
	v_cndmask_b32_e64 v102, v211, v102, s[24:25]
	v_cndmask_b32_e64 v101, v211, v101, s[22:23]
	v_cndmask_b32_e64 v100, v211, v100, s[20:21]
	v_cndmask_b32_e64 v99, v211, v99, s[18:19]
	v_cndmask_b32_e64 v98, v211, v98, s[16:17]
	v_cndmask_b32_e64 v97, v211, v97, s[14:15]
	v_cndmask_b32_e32 v96, v211, v96, vcc

; #define A_WAITBAR(N) asm volatile("s_waitcnt vmcnt(" #N ") lgkmcnt(0)\n\ts_barrier" ::: "memory")
; template <bool DIFF> ...
;     ...
;     for (int t = 0; t < NT; ++t) {
;         const int k3n = (k3 == 2) ? 0 : k3 + 1;
;         if (t + 1 < NT) A_DMA(t + 1, k3n, (t + 1) & 3);
;         if (late && pact) A_PV((t - 1) & 3);
;         const bool active = split ? ((t % NG) == grp) : (t <= my_lim);
;     ...
;         pact = active; k3 = k3n;
;         A_WAITBAR(0);
;     }
.LBB0_1493:
.LBB0_1495:
	s_add_i32 s0, s0, 64
	s_cmp_eq_u32 s80, s85
	s_cbranch_scc1 .Lattn_exit
	s_mov_b32 s14, s84
	s_mov_b32 s15, s85
	s_add_i32 s16, s14, 1
	s_cmp_lg_u32 s14, 2
	s_cselect_b32 s84, s16, 0
	s_mul_i32 s16, s14, 0x4400
	v_add_u32_e32 v0, s16, v148
	s_add_i32 s85, s15, 1
	s_and_b32 s77, s15, 3
	s_cmp_eq_u32 s77, s88
	s_cselect_b32 s16, 1, 0
	s_cmp_le_i32 s15, s82
	s_cselect_b32 s17, 1, 0
	s_and_b64 s[78:79], exec, s[2:3]
	s_cselect_b32 s15, s16, s17
	s_bitcmp1_b32 s15, 0
	s_cselect_b64 s[78:79], -1, 0
	s_and_b32 s16, s85, 3
	s_mulk_i32 s16, 0x5000
	s_add_i32 s18, s16, 0x8800
	s_mul_i32 s19, s84, 0x4400
	s_branch .LBB0_1480
